# grid barrier: XCD leader no longer bumps the unused per-XCD relay word (one atomic round trip off the leader path)
# speedup vs baseline: 1.0021x; 1.0021x over previous
.LBB0_2338:
	s_bcnt1_i32_b64 s4, s[4:5]
	v_mov_b32_e32 v0, s4
	v_mov_b32_e32 v1, 0x2000
	s_getpc_b64 s[98:99]
